# MFMA order + s_setprio removal extended to the three split-K tail K-loops (on top of v29)
# speedup vs baseline: 1.0025x; 1.0025x over previous
; #define PG8_STAGE(bufoff, gbase, voff) do { _Pragma("unroll") for (int _i = 0; _i < 2; ++_i) \
;         __builtin_amdgcn_global_load_lds((const unsigned*)((const char*)(gbase) + (voff)[_i]), (PG8_LAS unsigned*)(lds + (bufoff) + ldsw + _i * 8192), 16, 0, 0); } while (0)
; #define PG8_LDA(dst, b, h) do { _Pragma("unroll") for (int m = 0; m < 4; ++m) _Pragma("unroll") for (int k = 0; k < 2; ++k) dst[m][k] = *(const PG8_LAS bf16x8*)(lds + PG8_SA(b, h) + aoff + m * 2048 + k * 1024); } while (0)
; #define PG8_LDB(dst, b, h) do { _Pragma("unroll") for (int n = 0; n < 2; ++n) _Pragma("unroll") for (int k = 0; k < 2; ++k) dst[n][k] = *(const PG8_LAS bf16x8*)(lds + PG8_SB(b, h) + boff + n * 2048 + k * 1024); } while (0)
; #define PG8_MMA(ai, bj, At, Bt) do { __builtin_amdgcn_s_setprio(1); _Pragma("unroll") for (int m = 0; m < 4; ++m) _Pragma("unroll") for (int n = 0; n < 2; ++n) _Pragma("unroll") for (int k = 0; k < 2; ++k) \
;         acc[ai][bj][m][n] = __builtin_amdgcn_mfma_f32_16x16x32_bf16(Bt[n][k], At[m][k], acc[ai][bj][m][n], 0, 0, 0); __builtin_amdgcn_s_setprio(0); } while (0)
; #define PG8_WAIT_V(n) asm volatile("s_waitcnt vmcnt(" #n ")" ::: "memory")
; #define PG8_WAIT_L(n) asm volatile("s_waitcnt lgkmcnt(" #n ")" ::: "memory")
; #define PG8_BAR __builtin_amdgcn_s_barrier()
; #define PG8_SCHED __builtin_amdgcn_sched_barrier(0)
; template <class Epi, class Sched, bool ALIGN_EPI = false, bool SP2 = false>
; __device__ __forceinline__ void gemm_phase(PG8_LAS unsigned char* lds, const Gemm g, const Sched& S, const Epi& E) {
;     ...
;             PG8_LDB(B0, 0, 0); PG8_LDB(B1, 0, 1); PG8_SCHED; PG8_LDA(At, 0, 0); PG8_STAGE(PG8_SA(1, 1), a1 + hstep, voffA);
;             PG8_WAIT_V(8); PG8_WAIT_L(0); PG8_BAR; PG8_MMA(0, 0, At, B0); PG8_MMA(0, 1, At, B1); PG8_BAR; PG8_SCHED;
;             PG8_LDA(At, 0, 1); PG8_STAGE(PG8_SB(0, 0), b2, voffB); PG8_STAGE(PG8_SB(0, 1), b2 + hstep, voffB); PG8_STAGE(PG8_SA(0, 0), a2, voffA);
;             PG8_WAIT_V(8); PG8_WAIT_L(0); PG8_BAR; PG8_MMA(1, 0, At, B0); PG8_MMA(1, 1, At, B1); PG8_BAR; PG8_SCHED;
.LBB0_431:
	ds_read_b128 v[106:109], v101
	ds_read_b128 v[110:113], v101 offset:1024
	ds_read_b128 v[114:117], v101 offset:2048
	ds_read_b128 v[118:121], v101 offset:3072
	ds_read_b128 v[122:125], v102
	ds_read_b128 v[126:129], v102 offset:1024
	ds_read_b128 v[130:133], v102 offset:2048
	ds_read_b128 v[134:137], v102 offset:3072
	s_add_u32 s16, s14, 0xe6ea0080
	s_addc_u32 s17, s15, -1
	s_cmp_lg_u32 s37, 4
	s_cselect_b32 s16, s16, 0
	s_cselect_b32 s17, s17, 0
	s_add_u32 s18, s10, s16
	s_addc_u32 s19, s11, s17
	s_add_u32 s16, s8, s16
	s_addc_u32 s17, s9, s17
	s_mov_b32 m0, s38
	v_lshl_add_u64 v[158:159], v[96:97], 0, s[14:15]
	ds_read_b128 v[162:165], v103
	ds_read_b128 v[166:169], v103 offset:1024
	ds_read_b128 v[170:173], v103 offset:2048
	ds_read_b128 v[174:177], v103 offset:3072
	ds_read_b128 v[196:199], v103 offset:4096
	ds_read_b128 v[200:203], v103 offset:5120
	ds_read_b128 v[204:207], v103 offset:6144
	ds_read_b128 v[208:211], v103 offset:7168
	global_load_lds_dwordx4 v[158:159], off
	v_lshl_add_u64 v[158:159], v[98:99], 0, s[14:15]
	s_mov_b32 m0, s39
	s_nop 0
	global_load_lds_dwordx4 v[158:159], off
	s_waitcnt vmcnt(8)
	s_waitcnt lgkmcnt(0)
	s_barrier
	s_waitcnt lgkmcnt(0)
	v_mfma_f32_16x16x32_bf16 v[92:95], v[106:109], v[162:165], v[92:95]
	v_mfma_f32_16x16x32_bf16 v[92:95], v[110:113], v[166:169], v[92:95]
	v_mfma_f32_16x16x32_bf16 v[88:91], v[118:121], v[166:169], v[88:91]
	v_mfma_f32_16x16x32_bf16 v[88:91], v[114:117], v[162:165], v[88:91]
	v_mfma_f32_16x16x32_bf16 v[72:75], v[114:117], v[170:173], v[72:75]
	v_mfma_f32_16x16x32_bf16 v[72:75], v[118:121], v[174:177], v[72:75]
	v_mfma_f32_16x16x32_bf16 v[80:83], v[110:113], v[174:177], v[80:83]
	v_mfma_f32_16x16x32_bf16 v[80:83], v[106:109], v[170:173], v[80:83]
	v_mfma_f32_16x16x32_bf16 v[64:67], v[106:109], v[196:199], v[64:67]
	v_mfma_f32_16x16x32_bf16 v[64:67], v[110:113], v[200:203], v[64:67]
	v_mfma_f32_16x16x32_bf16 v[56:59], v[118:121], v[200:203], v[56:59]
	v_mfma_f32_16x16x32_bf16 v[56:59], v[114:117], v[196:199], v[56:59]
	v_mfma_f32_16x16x32_bf16 v[40:43], v[114:117], v[204:207], v[40:43]
	v_mfma_f32_16x16x32_bf16 v[40:43], v[118:121], v[208:211], v[40:43]
	v_mfma_f32_16x16x32_bf16 v[48:51], v[110:113], v[208:211], v[48:51]
	v_mfma_f32_16x16x32_bf16 v[48:51], v[106:109], v[204:207], v[48:51]
	v_mfma_f32_16x16x32_bf16 v[84:87], v[122:125], v[162:165], v[84:87]
	v_mfma_f32_16x16x32_bf16 v[84:87], v[126:129], v[166:169], v[84:87]
	v_mfma_f32_16x16x32_bf16 v[76:79], v[134:137], v[166:169], v[76:79]
	v_mfma_f32_16x16x32_bf16 v[76:79], v[130:133], v[162:165], v[76:79]
	v_mfma_f32_16x16x32_bf16 v[60:63], v[130:133], v[170:173], v[60:63]
	v_mfma_f32_16x16x32_bf16 v[60:63], v[134:137], v[174:177], v[60:63]
	v_mfma_f32_16x16x32_bf16 v[68:71], v[126:129], v[174:177], v[68:71]
	v_mfma_f32_16x16x32_bf16 v[68:71], v[122:125], v[170:173], v[68:71]
	v_mfma_f32_16x16x32_bf16 v[52:55], v[122:125], v[196:199], v[52:55]
	v_mfma_f32_16x16x32_bf16 v[52:55], v[126:129], v[200:203], v[52:55]
	v_mfma_f32_16x16x32_bf16 v[44:47], v[134:137], v[200:203], v[44:47]
	v_mfma_f32_16x16x32_bf16 v[44:47], v[130:133], v[196:199], v[44:47]
	v_mfma_f32_16x16x32_bf16 v[32:35], v[130:133], v[204:207], v[32:35]
	v_mfma_f32_16x16x32_bf16 v[32:35], v[134:137], v[208:211], v[32:35]
	v_mfma_f32_16x16x32_bf16 v[36:39], v[126:129], v[208:211], v[36:39]
	v_mfma_f32_16x16x32_bf16 v[36:39], v[122:125], v[204:207], v[36:39]
	s_barrier
	s_mov_b32 m0, s40
	v_lshl_add_u64 v[158:159], s[16:17], 0, v[144:145]
	s_add_u32 s48, s16, 0x160000
	ds_read_b128 v[162:165], v103 offset:16384
	ds_read_b128 v[166:169], v103 offset:17408
	ds_read_b128 v[170:173], v103 offset:18432
	ds_read_b128 v[174:177], v103 offset:19456
	global_load_lds_dwordx4 v[158:159], off
	v_lshl_add_u64 v[212:213], s[16:17], 0, v[148:149]
	s_mov_b32 m0, s41
	s_addc_u32 s49, s17, 0
	global_load_lds_dwordx4 v[212:213], off
	v_lshl_add_u64 v[196:197], s[48:49], 0, v[144:145]
	s_mov_b32 m0, s42
	v_lshl_add_u64 v[214:215], s[18:19], 0, v[142:143]
	global_load_lds_dwordx4 v[196:197], off
	v_lshl_add_u64 v[196:197], s[48:49], 0, v[148:149]
	s_mov_b32 m0, s43
	v_lshl_add_u64 v[216:217], s[18:19], 0, v[146:147]
	global_load_lds_dwordx4 v[196:197], off
	s_mov_b32 m0, s2
	s_nop 0
	global_load_lds_dwordx4 v[214:215], off
	s_mov_b32 m0, s3
	s_nop 0
	global_load_lds_dwordx4 v[216:217], off
	s_waitcnt vmcnt(8)
	s_waitcnt lgkmcnt(0)
	s_barrier
	s_waitcnt lgkmcnt(0)
	v_mfma_f32_16x16x32_bf16 v[28:31], v[106:109], v[162:165], v[28:31]
	v_mfma_f32_16x16x32_bf16 v[28:31], v[110:113], v[166:169], v[28:31]
	v_mfma_f32_16x16x32_bf16 v[24:27], v[118:121], v[166:169], v[24:27]
	v_mfma_f32_16x16x32_bf16 v[24:27], v[114:117], v[162:165], v[24:27]
	v_mfma_f32_16x16x32_bf16 v[12:15], v[106:109], v[170:173], v[12:15]
	v_mfma_f32_16x16x32_bf16 v[12:15], v[110:113], v[174:177], v[12:15]
	v_mfma_f32_16x16x32_bf16 v[8:11], v[118:121], v[174:177], v[8:11]
	v_mfma_f32_16x16x32_bf16 v[8:11], v[114:117], v[170:173], v[8:11]
	v_mfma_f32_16x16x32_bf16 v[20:23], v[122:125], v[162:165], v[20:23]
	v_mfma_f32_16x16x32_bf16 v[20:23], v[126:129], v[166:169], v[20:23]
	v_mfma_f32_16x16x32_bf16 v[16:19], v[134:137], v[166:169], v[16:19]
	v_mfma_f32_16x16x32_bf16 v[16:19], v[130:133], v[162:165], v[16:19]
	v_mfma_f32_16x16x32_bf16 v[4:7], v[122:125], v[170:173], v[4:7]
	v_mfma_f32_16x16x32_bf16 v[4:7], v[126:129], v[174:177], v[4:7]
	v_mfma_f32_16x16x32_bf16 v[0:3], v[134:137], v[174:177], v[0:3]
	v_mfma_f32_16x16x32_bf16 v[0:3], v[130:133], v[170:173], v[0:3]
	s_barrier
; #define PG8_STAGE(bufoff, gbase, voff) do { _Pragma("unroll") for (int _i = 0; _i < 2; ++_i) \
;         __builtin_amdgcn_global_load_lds((const unsigned*)((const char*)(gbase) + (voff)[_i]), (PG8_LAS unsigned*)(lds + (bufoff) + ldsw + _i * 8192), 16, 0, 0); } while (0)
; #define PG8_LDA(dst, b, h) do { _Pragma("unroll") for (int m = 0; m < 4; ++m) _Pragma("unroll") for (int k = 0; k < 2; ++k) dst[m][k] = *(const PG8_LAS bf16x8*)(lds + PG8_SA(b, h) + aoff + m * 2048 + k * 1024); } while (0)
; #define PG8_LDB(dst, b, h) do { _Pragma("unroll") for (int n = 0; n < 2; ++n) _Pragma("unroll") for (int k = 0; k < 2; ++k) dst[n][k] = *(const PG8_LAS bf16x8*)(lds + PG8_SB(b, h) + boff + n * 2048 + k * 1024); } while (0)
; #define PG8_MMA(ai, bj, At, Bt) do { __builtin_amdgcn_s_setprio(1); _Pragma("unroll") for (int m = 0; m < 4; ++m) _Pragma("unroll") for (int n = 0; n < 2; ++n) _Pragma("unroll") for (int k = 0; k < 2; ++k) \
;         acc[ai][bj][m][n] = __builtin_amdgcn_mfma_f32_16x16x32_bf16(Bt[n][k], At[m][k], acc[ai][bj][m][n], 0, 0, 0); __builtin_amdgcn_s_setprio(0); } while (0)
; #define PG8_WAIT_V(n) asm volatile("s_waitcnt vmcnt(" #n ")" ::: "memory")
; #define PG8_WAIT_L(n) asm volatile("s_waitcnt lgkmcnt(" #n ")" ::: "memory")
; #define PG8_BAR __builtin_amdgcn_s_barrier()
; #define PG8_SCHED __builtin_amdgcn_sched_barrier(0)
; template <class Epi, class Sched, bool ALIGN_EPI = false, bool SP2 = false>
; __device__ __forceinline__ void gemm_phase(PG8_LAS unsigned char* lds, const Gemm g, const Sched& S, const Epi& E) {
;     ...
;             PG8_LDB(B0, 1, 0); PG8_LDB(B1, 1, 1); PG8_SCHED; PG8_LDA(At, 1, 0); PG8_STAGE(PG8_SA(0, 1), a2 + hstep, voffA);
;             PG8_WAIT_V(8); PG8_WAIT_L(0); PG8_BAR; PG8_MMA(0, 0, At, B0); PG8_MMA(0, 1, At, B1); PG8_BAR; PG8_SCHED;
;             PG8_LDA(At, 1, 1); PG8_STAGE(PG8_SB(1, 0), b3, voffB); PG8_STAGE(PG8_SB(1, 1), b3 + hstep, voffB); PG8_STAGE(PG8_SA(1, 0), a3, voffA);
;             PG8_WAIT_V(8); PG8_WAIT_L(0); PG8_BAR; PG8_MMA(1, 0, At, B0); PG8_MMA(1, 1, At, B1); PG8_BAR; PG8_SCHED;
	ds_read_b128 v[106:109], v104
	ds_read_b128 v[110:113], v104 offset:1024
	ds_read_b128 v[114:117], v104 offset:2048
	ds_read_b128 v[118:121], v104 offset:3072
	ds_read_b128 v[122:125], v105
	ds_read_b128 v[126:129], v105 offset:1024
	ds_read_b128 v[130:133], v105 offset:2048
	ds_read_b128 v[134:137], v105 offset:3072
	s_add_u32 s18, s18, 0x160000
	s_addc_u32 s19, s19, 0
	s_mov_b32 m0, s7
	v_lshl_add_u64 v[218:219], s[18:19], 0, v[142:143]
	ds_read_b128 v[162:165], v103 offset:32768
	ds_read_b128 v[166:169], v103 offset:33792
	ds_read_b128 v[170:173], v103 offset:34816
	ds_read_b128 v[174:177], v103 offset:35840
	ds_read_b128 v[196:199], v103 offset:36864
	ds_read_b128 v[200:203], v103 offset:37888
	ds_read_b128 v[204:207], v103 offset:38912
	ds_read_b128 v[208:211], v103 offset:39936
	global_load_lds_dwordx4 v[218:219], off
	v_lshl_add_u64 v[218:219], s[18:19], 0, v[146:147]
	s_mov_b32 m0, s33
	s_nop 0
	global_load_lds_dwordx4 v[218:219], off
	s_waitcnt vmcnt(8)
	s_waitcnt lgkmcnt(0)
	s_barrier
	s_waitcnt lgkmcnt(0)
	v_mfma_f32_16x16x32_bf16 v[92:95], v[106:109], v[162:165], v[92:95]
	v_mfma_f32_16x16x32_bf16 v[92:95], v[110:113], v[166:169], v[92:95]
	v_mfma_f32_16x16x32_bf16 v[88:91], v[118:121], v[166:169], v[88:91]
	v_mfma_f32_16x16x32_bf16 v[88:91], v[114:117], v[162:165], v[88:91]
	v_mfma_f32_16x16x32_bf16 v[72:75], v[114:117], v[170:173], v[72:75]
	v_mfma_f32_16x16x32_bf16 v[72:75], v[118:121], v[174:177], v[72:75]
	v_mfma_f32_16x16x32_bf16 v[80:83], v[110:113], v[174:177], v[80:83]
	v_mfma_f32_16x16x32_bf16 v[80:83], v[106:109], v[170:173], v[80:83]
	v_mfma_f32_16x16x32_bf16 v[64:67], v[106:109], v[196:199], v[64:67]
	v_mfma_f32_16x16x32_bf16 v[64:67], v[110:113], v[200:203], v[64:67]
	v_mfma_f32_16x16x32_bf16 v[56:59], v[118:121], v[200:203], v[56:59]
	v_mfma_f32_16x16x32_bf16 v[56:59], v[114:117], v[196:199], v[56:59]
	v_mfma_f32_16x16x32_bf16 v[40:43], v[114:117], v[204:207], v[40:43]
	v_mfma_f32_16x16x32_bf16 v[40:43], v[118:121], v[208:211], v[40:43]
	v_mfma_f32_16x16x32_bf16 v[48:51], v[110:113], v[208:211], v[48:51]
	v_mfma_f32_16x16x32_bf16 v[48:51], v[106:109], v[204:207], v[48:51]
	v_mfma_f32_16x16x32_bf16 v[84:87], v[122:125], v[162:165], v[84:87]
	v_mfma_f32_16x16x32_bf16 v[84:87], v[126:129], v[166:169], v[84:87]
	v_mfma_f32_16x16x32_bf16 v[76:79], v[134:137], v[166:169], v[76:79]
	v_mfma_f32_16x16x32_bf16 v[76:79], v[130:133], v[162:165], v[76:79]
	v_mfma_f32_16x16x32_bf16 v[60:63], v[130:133], v[170:173], v[60:63]
	v_mfma_f32_16x16x32_bf16 v[60:63], v[134:137], v[174:177], v[60:63]
	v_mfma_f32_16x16x32_bf16 v[68:71], v[126:129], v[174:177], v[68:71]
	v_mfma_f32_16x16x32_bf16 v[68:71], v[122:125], v[170:173], v[68:71]
	v_mfma_f32_16x16x32_bf16 v[52:55], v[122:125], v[196:199], v[52:55]
	v_mfma_f32_16x16x32_bf16 v[52:55], v[126:129], v[200:203], v[52:55]
	v_mfma_f32_16x16x32_bf16 v[44:47], v[134:137], v[200:203], v[44:47]
	v_mfma_f32_16x16x32_bf16 v[44:47], v[130:133], v[196:199], v[44:47]
	v_mfma_f32_16x16x32_bf16 v[32:35], v[130:133], v[204:207], v[32:35]
	v_mfma_f32_16x16x32_bf16 v[32:35], v[134:137], v[208:211], v[32:35]
	v_mfma_f32_16x16x32_bf16 v[36:39], v[126:129], v[208:211], v[36:39]
	v_mfma_f32_16x16x32_bf16 v[36:39], v[122:125], v[204:207], v[36:39]
	s_barrier
	s_mov_b32 m0, s44
	v_lshl_add_u64 v[158:159], v[158:159], 0, s[12:13]
	s_add_u32 s16, s16, 0x160080
	ds_read_b128 v[162:165], v103 offset:49152
	ds_read_b128 v[166:169], v103 offset:50176
	ds_read_b128 v[170:173], v103 offset:51200
	ds_read_b128 v[174:177], v103 offset:52224
	global_load_lds_dwordx4 v[158:159], off
	v_lshl_add_u64 v[158:159], v[212:213], 0, s[12:13]
	s_mov_b32 m0, s45
	s_addc_u32 s17, s17, 0
	global_load_lds_dwordx4 v[158:159], off
	v_lshl_add_u64 v[158:159], s[16:17], 0, v[144:145]
	s_mov_b32 m0, s46
	s_nop 0
	global_load_lds_dwordx4 v[158:159], off
	v_lshl_add_u64 v[158:159], s[16:17], 0, v[148:149]
	s_mov_b32 m0, s47
	s_nop 0
	global_load_lds_dwordx4 v[158:159], off
	v_lshl_add_u64 v[158:159], v[214:215], 0, s[12:13]
	s_mov_b32 m0, s35
	s_nop 0
	global_load_lds_dwordx4 v[158:159], off
	v_lshl_add_u64 v[158:159], v[216:217], 0, s[12:13]
	s_mov_b32 m0, s36
	s_nop 0
	global_load_lds_dwordx4 v[158:159], off
	s_waitcnt vmcnt(8)
	s_waitcnt lgkmcnt(0)
	s_barrier
	s_waitcnt lgkmcnt(0)
	v_mfma_f32_16x16x32_bf16 v[28:31], v[106:109], v[162:165], v[28:31]
	v_mfma_f32_16x16x32_bf16 v[28:31], v[110:113], v[166:169], v[28:31]
	v_mfma_f32_16x16x32_bf16 v[24:27], v[118:121], v[166:169], v[24:27]
	v_mfma_f32_16x16x32_bf16 v[24:27], v[114:117], v[162:165], v[24:27]
	v_mfma_f32_16x16x32_bf16 v[12:15], v[106:109], v[170:173], v[12:15]
	v_mfma_f32_16x16x32_bf16 v[12:15], v[110:113], v[174:177], v[12:15]
	v_mfma_f32_16x16x32_bf16 v[8:11], v[118:121], v[174:177], v[8:11]
	v_mfma_f32_16x16x32_bf16 v[8:11], v[114:117], v[170:173], v[8:11]
	v_mfma_f32_16x16x32_bf16 v[20:23], v[122:125], v[162:165], v[20:23]
	v_mfma_f32_16x16x32_bf16 v[20:23], v[126:129], v[166:169], v[20:23]
	v_mfma_f32_16x16x32_bf16 v[16:19], v[134:137], v[166:169], v[16:19]
	v_mfma_f32_16x16x32_bf16 v[16:19], v[130:133], v[162:165], v[16:19]
	v_mfma_f32_16x16x32_bf16 v[4:7], v[122:125], v[170:173], v[4:7]
	v_mfma_f32_16x16x32_bf16 v[4:7], v[126:129], v[174:177], v[4:7]
	v_mfma_f32_16x16x32_bf16 v[0:3], v[134:137], v[174:177], v[0:3]
	v_mfma_f32_16x16x32_bf16 v[0:3], v[130:133], v[170:173], v[0:3]
	s_barrier
	s_add_i32 s37, s37, 2
	s_add_u32 s14, s14, 0x100
	s_addc_u32 s15, s15, 0
	s_cmp_gt_u32 s37, 5
	s_cbranch_scc0 .LBB0_431
	s_cmpk_lt_u32 s26, 0x100
	s_cbranch_scc0 .LBB0_434
	s_barrier

; #define PG8_STAGE(bufoff, gbase, voff) do { _Pragma("unroll") for (int _i = 0; _i < 2; ++_i) \
;         __builtin_amdgcn_global_load_lds((const unsigned*)((const char*)(gbase) + (voff)[_i]), (PG8_LAS unsigned*)(lds + (bufoff) + ldsw + _i * 8192), 16, 0, 0); } while (0)
; #define PG8_LDA(dst, b, h) do { _Pragma("unroll") for (int m = 0; m < 4; ++m) _Pragma("unroll") for (int k = 0; k < 2; ++k) dst[m][k] = *(const PG8_LAS bf16x8*)(lds + PG8_SA(b, h) + aoff + m * 2048 + k * 1024); } while (0)
; #define PG8_LDB(dst, b, h) do { _Pragma("unroll") for (int n = 0; n < 2; ++n) _Pragma("unroll") for (int k = 0; k < 2; ++k) dst[n][k] = *(const PG8_LAS bf16x8*)(lds + PG8_SB(b, h) + boff + n * 2048 + k * 1024); } while (0)
; #define PG8_MMA(ai, bj, At, Bt) do { __builtin_amdgcn_s_setprio(1); _Pragma("unroll") for (int m = 0; m < 4; ++m) _Pragma("unroll") for (int n = 0; n < 2; ++n) _Pragma("unroll") for (int k = 0; k < 2; ++k) \
;         acc[ai][bj][m][n] = __builtin_amdgcn_mfma_f32_16x16x32_bf16(Bt[n][k], At[m][k], acc[ai][bj][m][n], 0, 0, 0); __builtin_amdgcn_s_setprio(0); } while (0)
; #define PG8_WAIT_V(n) asm volatile("s_waitcnt vmcnt(" #n ")" ::: "memory")
; #define PG8_BAR __builtin_amdgcn_s_barrier()
; template <class Epi, class Sched, bool ALIGN_EPI = false, bool SP2 = false>
; __device__ __forceinline__ void gemm_phase(PG8_LAS unsigned char* lds, const Gemm g, const Sched& S, const Epi& E) {
;     ...
;         for (int t = 0; t < nt; t += 2) {
;             const bool last = (t == nt - 2);
;             const char* a1 = cA + (size_t)(t + 1) * kstep;
;             const char* a2 = last ? nA : cA + (size_t)(t + 2) * kstep; const char* b2 = last ? nB : cB + (size_t)(t + 2) * kstep;
;             const char* a3 = a2 + kstep; const char* b3 = b2 + kstep;
;             if (last && has_next) S.a_ready(nxt);
;             if constexpr (SP2) {
;             PG8_LDB(B0, 0, 0); PG8_LDB(B1, 0, 1); PG8_SCHED; PG8_LDA(At, 0, 0); PG8_STAGE(PG8_SA(1, 1), a1 + hstep, voffA);
;             PG8_WAIT_V(8); PG8_WAIT_L(0); PG8_BAR; PG8_MMA(0, 0, At, B0); PG8_MMA(0, 1, At, B1); PG8_BAR; PG8_SCHED;
;             PG8_LDA(At, 0, 1); PG8_STAGE(PG8_SB(0, 0), b2, voffB); PG8_STAGE(PG8_SB(0, 1), b2 + hstep, voffB); PG8_STAGE(PG8_SA(0, 0), a2, voffA);
;             PG8_WAIT_V(8); PG8_WAIT_L(0); PG8_BAR; PG8_MMA(1, 0, At, B0); PG8_MMA(1, 1, At, B1); PG8_BAR; PG8_SCHED;
.LBB0_1135:
	s_add_i32 s22, s26, 0x100
	s_and_b64 s[20:21], s[20:21], exec
	s_cselect_b32 s21, 0, s22
	s_cselect_b32 s20, 0, 0
	s_add_u32 s22, s12, s21
	ds_read_b128 v[102:105], v96
	ds_read_b128 v[106:109], v96 offset:1024
	ds_read_b128 v[110:113], v96 offset:2048
	ds_read_b128 v[114:117], v96 offset:3072
	ds_read_b128 v[118:121], v97
	ds_read_b128 v[122:125], v97 offset:1024
	ds_read_b128 v[126:129], v97 offset:2048
	ds_read_b128 v[130:133], v97 offset:3072
	s_addc_u32 s23, s13, s20
	s_add_u32 s24, s10, s21
	s_addc_u32 s25, s11, s20
	s_add_u32 s30, s14, s26
	s_addc_u32 s31, s15, 0
	s_add_u32 s26, s24, 0x80000
	s_addc_u32 s27, s25, 0
	s_add_u32 s20, s22, 0x80000
	s_addc_u32 s21, s23, 0
	s_add_u32 s28, s24, 0x80080
	s_addc_u32 s29, s25, 0
	v_lshl_add_u64 v[160:161], s[30:31], 0, v[150:151]
	s_mov_b32 m0, s37
	v_lshl_add_u64 v[160:161], v[160:161], 0, s[16:17]
	ds_read_b128 v[134:137], v99
	ds_read_b128 v[164:167], v99 offset:1024
	ds_read_b128 v[168:171], v99 offset:2048
	ds_read_b128 v[172:175], v99 offset:3072
	ds_read_b128 v[188:191], v99 offset:4096
	ds_read_b128 v[192:195], v99 offset:5120
	ds_read_b128 v[196:199], v99 offset:6144
	ds_read_b128 v[200:203], v99 offset:7168
	global_load_lds_dwordx4 v[160:161], off
	v_lshl_add_u64 v[160:161], s[30:31], 0, v[154:155]
	v_lshl_add_u64 v[160:161], v[160:161], 0, s[16:17]
	s_mov_b32 m0, s38
	s_nop 0
	global_load_lds_dwordx4 v[160:161], off
	s_waitcnt vmcnt(8)
	s_waitcnt lgkmcnt(0)
	s_barrier
	s_waitcnt lgkmcnt(0)
	v_mfma_f32_16x16x32_bf16 v[92:95], v[102:105], v[134:137], v[92:95]
	v_mfma_f32_16x16x32_bf16 v[92:95], v[106:109], v[164:167], v[92:95]
	v_mfma_f32_16x16x32_bf16 v[88:91], v[114:117], v[164:167], v[88:91]
	v_mfma_f32_16x16x32_bf16 v[88:91], v[110:113], v[134:137], v[88:91]
	v_mfma_f32_16x16x32_bf16 v[80:83], v[110:113], v[168:171], v[80:83]
	v_mfma_f32_16x16x32_bf16 v[80:83], v[114:117], v[172:175], v[80:83]
	v_mfma_f32_16x16x32_bf16 v[84:87], v[106:109], v[172:175], v[84:87]
	v_mfma_f32_16x16x32_bf16 v[84:87], v[102:105], v[168:171], v[84:87]
	v_mfma_f32_16x16x32_bf16 v[68:71], v[102:105], v[188:191], v[68:71]
	v_mfma_f32_16x16x32_bf16 v[68:71], v[106:109], v[192:195], v[68:71]
	v_mfma_f32_16x16x32_bf16 v[64:67], v[114:117], v[192:195], v[64:67]
	v_mfma_f32_16x16x32_bf16 v[64:67], v[110:113], v[188:191], v[64:67]
	v_mfma_f32_16x16x32_bf16 v[48:51], v[110:113], v[196:199], v[48:51]
	v_mfma_f32_16x16x32_bf16 v[48:51], v[114:117], v[200:203], v[48:51]
	v_mfma_f32_16x16x32_bf16 v[52:55], v[106:109], v[200:203], v[52:55]
	v_mfma_f32_16x16x32_bf16 v[52:55], v[102:105], v[196:199], v[52:55]
	v_mfma_f32_16x16x32_bf16 v[76:79], v[118:121], v[134:137], v[76:79]
	v_mfma_f32_16x16x32_bf16 v[76:79], v[122:125], v[164:167], v[76:79]
	v_mfma_f32_16x16x32_bf16 v[72:75], v[130:133], v[164:167], v[72:75]
	v_mfma_f32_16x16x32_bf16 v[72:75], v[126:129], v[134:137], v[72:75]
	v_mfma_f32_16x16x32_bf16 v[56:59], v[126:129], v[168:171], v[56:59]
	v_mfma_f32_16x16x32_bf16 v[56:59], v[130:133], v[172:175], v[56:59]
	v_mfma_f32_16x16x32_bf16 v[60:63], v[122:125], v[172:175], v[60:63]
	v_mfma_f32_16x16x32_bf16 v[60:63], v[118:121], v[168:171], v[60:63]
	v_mfma_f32_16x16x32_bf16 v[44:47], v[118:121], v[188:191], v[44:47]
	v_mfma_f32_16x16x32_bf16 v[44:47], v[122:125], v[192:195], v[44:47]
	v_mfma_f32_16x16x32_bf16 v[40:43], v[130:133], v[192:195], v[40:43]
	v_mfma_f32_16x16x32_bf16 v[40:43], v[126:129], v[188:191], v[40:43]
	v_mfma_f32_16x16x32_bf16 v[32:35], v[126:129], v[196:199], v[32:35]
	v_mfma_f32_16x16x32_bf16 v[32:35], v[130:133], v[200:203], v[32:35]
	v_mfma_f32_16x16x32_bf16 v[36:39], v[122:125], v[200:203], v[36:39]
	v_mfma_f32_16x16x32_bf16 v[36:39], v[118:121], v[196:199], v[36:39]
	s_barrier
	s_mov_b32 m0, s39
	v_lshl_add_u64 v[160:161], s[24:25], 0, v[152:153]
	ds_read_b128 v[134:137], v99 offset:16384
	ds_read_b128 v[164:167], v99 offset:17408
	ds_read_b128 v[168:171], v99 offset:18432
	ds_read_b128 v[172:175], v99 offset:19456
	global_load_lds_dwordx4 v[160:161], off
	v_lshl_add_u64 v[176:177], s[24:25], 0, v[156:157]
	s_mov_b32 m0, s40
	v_lshl_add_u64 v[188:189], s[26:27], 0, v[152:153]
	global_load_lds_dwordx4 v[176:177], off
	s_mov_b32 m0, s41
	v_lshl_add_u64 v[204:205], s[22:23], 0, v[150:151]
	global_load_lds_dwordx4 v[188:189], off
	v_lshl_add_u64 v[188:189], s[26:27], 0, v[156:157]
	s_mov_b32 m0, s42
	v_lshl_add_u64 v[206:207], s[22:23], 0, v[154:155]
	global_load_lds_dwordx4 v[188:189], off
	s_mov_b32 m0, s2
	s_nop 0
	global_load_lds_dwordx4 v[204:205], off
	s_mov_b32 m0, s3
	s_nop 0
	global_load_lds_dwordx4 v[206:207], off
	s_waitcnt vmcnt(8)
	s_waitcnt lgkmcnt(0)
	s_barrier
	s_waitcnt lgkmcnt(0)
	v_mfma_f32_16x16x32_bf16 v[28:31], v[102:105], v[134:137], v[28:31]
	v_mfma_f32_16x16x32_bf16 v[28:31], v[106:109], v[164:167], v[28:31]
	v_mfma_f32_16x16x32_bf16 v[24:27], v[114:117], v[164:167], v[24:27]
	v_mfma_f32_16x16x32_bf16 v[24:27], v[110:113], v[134:137], v[24:27]
	v_mfma_f32_16x16x32_bf16 v[12:15], v[102:105], v[168:171], v[12:15]
	v_mfma_f32_16x16x32_bf16 v[12:15], v[106:109], v[172:175], v[12:15]
	v_mfma_f32_16x16x32_bf16 v[8:11], v[114:117], v[172:175], v[8:11]
	v_mfma_f32_16x16x32_bf16 v[8:11], v[110:113], v[168:171], v[8:11]
	v_mfma_f32_16x16x32_bf16 v[20:23], v[118:121], v[134:137], v[20:23]
	v_mfma_f32_16x16x32_bf16 v[20:23], v[122:125], v[164:167], v[20:23]
	v_mfma_f32_16x16x32_bf16 v[16:19], v[130:133], v[164:167], v[16:19]
	v_mfma_f32_16x16x32_bf16 v[16:19], v[126:129], v[134:137], v[16:19]
	v_mfma_f32_16x16x32_bf16 v[4:7], v[118:121], v[168:171], v[4:7]
	v_mfma_f32_16x16x32_bf16 v[4:7], v[122:125], v[172:175], v[4:7]
	v_mfma_f32_16x16x32_bf16 v[0:3], v[130:133], v[172:175], v[0:3]
	v_mfma_f32_16x16x32_bf16 v[0:3], v[126:129], v[168:171], v[0:3]
	s_barrier
; #define PG8_STAGE(bufoff, gbase, voff) do { _Pragma("unroll") for (int _i = 0; _i < 2; ++_i) \
;         __builtin_amdgcn_global_load_lds((const unsigned*)((const char*)(gbase) + (voff)[_i]), (PG8_LAS unsigned*)(lds + (bufoff) + ldsw + _i * 8192), 16, 0, 0); } while (0)
; #define PG8_LDA(dst, b, h) do { _Pragma("unroll") for (int m = 0; m < 4; ++m) _Pragma("unroll") for (int k = 0; k < 2; ++k) dst[m][k] = *(const PG8_LAS bf16x8*)(lds + PG8_SA(b, h) + aoff + m * 2048 + k * 1024); } while (0)
; #define PG8_LDB(dst, b, h) do { _Pragma("unroll") for (int n = 0; n < 2; ++n) _Pragma("unroll") for (int k = 0; k < 2; ++k) dst[n][k] = *(const PG8_LAS bf16x8*)(lds + PG8_SB(b, h) + boff + n * 2048 + k * 1024); } while (0)
; #define PG8_MMA(ai, bj, At, Bt) do { __builtin_amdgcn_s_setprio(1); _Pragma("unroll") for (int m = 0; m < 4; ++m) _Pragma("unroll") for (int n = 0; n < 2; ++n) _Pragma("unroll") for (int k = 0; k < 2; ++k) \
;         acc[ai][bj][m][n] = __builtin_amdgcn_mfma_f32_16x16x32_bf16(Bt[n][k], At[m][k], acc[ai][bj][m][n], 0, 0, 0); __builtin_amdgcn_s_setprio(0); } while (0)
; #define PG8_WAIT_V(n) asm volatile("s_waitcnt vmcnt(" #n ")" ::: "memory")
; #define PG8_WAIT_L(n) asm volatile("s_waitcnt lgkmcnt(" #n ")" ::: "memory")
; #define PG8_BAR __builtin_amdgcn_s_barrier()
; #define PG8_SCHED __builtin_amdgcn_sched_barrier(0)
; template <class Epi, class Sched, bool ALIGN_EPI = false, bool SP2 = false>
; __device__ __forceinline__ void gemm_phase(PG8_LAS unsigned char* lds, const Gemm g, const Sched& S, const Epi& E) {
;     ...
;             PG8_LDB(B0, 1, 0); PG8_LDB(B1, 1, 1); PG8_SCHED; PG8_LDA(At, 1, 0); PG8_STAGE(PG8_SA(0, 1), a2 + hstep, voffA);
;             PG8_WAIT_V(8); PG8_WAIT_L(0); PG8_BAR; PG8_MMA(0, 0, At, B0); PG8_MMA(0, 1, At, B1); PG8_BAR; PG8_SCHED;
;             PG8_LDA(At, 1, 1); PG8_STAGE(PG8_SB(1, 0), b3, voffB); PG8_STAGE(PG8_SB(1, 1), b3 + hstep, voffB); PG8_STAGE(PG8_SA(1, 0), a3, voffA);
;             PG8_WAIT_V(8); PG8_WAIT_L(0); PG8_BAR; PG8_MMA(1, 0, At, B0); PG8_MMA(1, 1, At, B1); PG8_BAR; PG8_SCHED;
;     ...
;         if constexpr (ALIGN_EPI) { if (wr == 0) PG8_BAR; }
	ds_read_b128 v[102:105], v100
	ds_read_b128 v[106:109], v100 offset:1024
	ds_read_b128 v[110:113], v100 offset:2048
	ds_read_b128 v[114:117], v100 offset:3072
	ds_read_b128 v[118:121], v101
	ds_read_b128 v[122:125], v101 offset:1024
	ds_read_b128 v[126:129], v101 offset:2048
	ds_read_b128 v[130:133], v101 offset:3072
	s_mov_b32 m0, s7
	v_lshl_add_u64 v[208:209], s[20:21], 0, v[150:151]
	ds_read_b128 v[134:137], v99 offset:32768
	ds_read_b128 v[164:167], v99 offset:33792
	ds_read_b128 v[168:171], v99 offset:34816
	ds_read_b128 v[172:175], v99 offset:35840
	ds_read_b128 v[188:191], v99 offset:36864
	ds_read_b128 v[192:195], v99 offset:37888
	ds_read_b128 v[196:199], v99 offset:38912
	ds_read_b128 v[200:203], v99 offset:39936
	global_load_lds_dwordx4 v[208:209], off
	v_lshl_add_u64 v[208:209], s[20:21], 0, v[154:155]
	s_mov_b32 m0, s9
	s_nop 0
	global_load_lds_dwordx4 v[208:209], off
	s_waitcnt vmcnt(8)
	s_waitcnt lgkmcnt(0)
	s_barrier
	s_waitcnt lgkmcnt(0)
	v_mfma_f32_16x16x32_bf16 v[92:95], v[102:105], v[134:137], v[92:95]
	v_mfma_f32_16x16x32_bf16 v[92:95], v[106:109], v[164:167], v[92:95]
	v_mfma_f32_16x16x32_bf16 v[88:91], v[114:117], v[164:167], v[88:91]
	v_mfma_f32_16x16x32_bf16 v[88:91], v[110:113], v[134:137], v[88:91]
	v_mfma_f32_16x16x32_bf16 v[80:83], v[110:113], v[168:171], v[80:83]
	v_mfma_f32_16x16x32_bf16 v[80:83], v[114:117], v[172:175], v[80:83]
	v_mfma_f32_16x16x32_bf16 v[84:87], v[106:109], v[172:175], v[84:87]
	v_mfma_f32_16x16x32_bf16 v[84:87], v[102:105], v[168:171], v[84:87]
	v_mfma_f32_16x16x32_bf16 v[68:71], v[102:105], v[188:191], v[68:71]
	v_mfma_f32_16x16x32_bf16 v[68:71], v[106:109], v[192:195], v[68:71]
	v_mfma_f32_16x16x32_bf16 v[64:67], v[114:117], v[192:195], v[64:67]
	v_mfma_f32_16x16x32_bf16 v[64:67], v[110:113], v[188:191], v[64:67]
	v_mfma_f32_16x16x32_bf16 v[48:51], v[110:113], v[196:199], v[48:51]
	v_mfma_f32_16x16x32_bf16 v[48:51], v[114:117], v[200:203], v[48:51]
	v_mfma_f32_16x16x32_bf16 v[52:55], v[106:109], v[200:203], v[52:55]
	v_mfma_f32_16x16x32_bf16 v[52:55], v[102:105], v[196:199], v[52:55]
	v_mfma_f32_16x16x32_bf16 v[76:79], v[118:121], v[134:137], v[76:79]
	v_mfma_f32_16x16x32_bf16 v[76:79], v[122:125], v[164:167], v[76:79]
	v_mfma_f32_16x16x32_bf16 v[72:75], v[130:133], v[164:167], v[72:75]
	v_mfma_f32_16x16x32_bf16 v[72:75], v[126:129], v[134:137], v[72:75]
	v_mfma_f32_16x16x32_bf16 v[56:59], v[126:129], v[168:171], v[56:59]
	v_mfma_f32_16x16x32_bf16 v[56:59], v[130:133], v[172:175], v[56:59]
	v_mfma_f32_16x16x32_bf16 v[60:63], v[122:125], v[172:175], v[60:63]
	v_mfma_f32_16x16x32_bf16 v[60:63], v[118:121], v[168:171], v[60:63]
	v_mfma_f32_16x16x32_bf16 v[44:47], v[118:121], v[188:191], v[44:47]
	v_mfma_f32_16x16x32_bf16 v[44:47], v[122:125], v[192:195], v[44:47]
	v_mfma_f32_16x16x32_bf16 v[40:43], v[130:133], v[192:195], v[40:43]
	v_mfma_f32_16x16x32_bf16 v[40:43], v[126:129], v[188:191], v[40:43]
	v_mfma_f32_16x16x32_bf16 v[32:35], v[126:129], v[196:199], v[32:35]
	v_mfma_f32_16x16x32_bf16 v[32:35], v[130:133], v[200:203], v[32:35]
	v_mfma_f32_16x16x32_bf16 v[36:39], v[122:125], v[200:203], v[36:39]
	v_mfma_f32_16x16x32_bf16 v[36:39], v[118:121], v[196:199], v[36:39]
	s_barrier
	s_mov_b32 m0, s43
	v_lshl_add_u64 v[160:161], v[160:161], 0, s[16:17]
	ds_read_b128 v[134:137], v99 offset:49152
	ds_read_b128 v[164:167], v99 offset:50176
	ds_read_b128 v[168:171], v99 offset:51200
	ds_read_b128 v[172:175], v99 offset:52224
	global_load_lds_dwordx4 v[160:161], off
	v_lshl_add_u64 v[160:161], v[176:177], 0, s[16:17]
	s_mov_b32 m0, s44
	s_nop 0
	global_load_lds_dwordx4 v[160:161], off
	v_lshl_add_u64 v[160:161], s[28:29], 0, v[152:153]
	s_mov_b32 m0, s45
	s_nop 0
	global_load_lds_dwordx4 v[160:161], off
	v_lshl_add_u64 v[160:161], s[28:29], 0, v[156:157]
	s_mov_b32 m0, s46
	s_nop 0
	global_load_lds_dwordx4 v[160:161], off
	v_lshl_add_u64 v[160:161], v[204:205], 0, s[16:17]
	s_mov_b32 m0, s35
	s_nop 0
	global_load_lds_dwordx4 v[160:161], off
	v_lshl_add_u64 v[160:161], v[206:207], 0, s[16:17]
	s_mov_b32 m0, s36
	s_nop 0
	global_load_lds_dwordx4 v[160:161], off
	s_waitcnt vmcnt(8)
	s_waitcnt lgkmcnt(0)
	s_barrier
	s_waitcnt lgkmcnt(0)
	v_mfma_f32_16x16x32_bf16 v[28:31], v[102:105], v[134:137], v[28:31]
	v_mfma_f32_16x16x32_bf16 v[28:31], v[106:109], v[164:167], v[28:31]
	v_mfma_f32_16x16x32_bf16 v[24:27], v[114:117], v[164:167], v[24:27]
	v_mfma_f32_16x16x32_bf16 v[24:27], v[110:113], v[134:137], v[24:27]
	v_mfma_f32_16x16x32_bf16 v[12:15], v[102:105], v[168:171], v[12:15]
	v_mfma_f32_16x16x32_bf16 v[12:15], v[106:109], v[172:175], v[12:15]
	v_mfma_f32_16x16x32_bf16 v[8:11], v[114:117], v[172:175], v[8:11]
	v_mfma_f32_16x16x32_bf16 v[8:11], v[110:113], v[168:171], v[8:11]
	v_mfma_f32_16x16x32_bf16 v[20:23], v[118:121], v[134:137], v[20:23]
	v_mfma_f32_16x16x32_bf16 v[20:23], v[122:125], v[164:167], v[20:23]
	v_mfma_f32_16x16x32_bf16 v[16:19], v[130:133], v[164:167], v[16:19]
	v_mfma_f32_16x16x32_bf16 v[16:19], v[126:129], v[134:137], v[16:19]
	v_mfma_f32_16x16x32_bf16 v[4:7], v[118:121], v[168:171], v[4:7]
	v_mfma_f32_16x16x32_bf16 v[4:7], v[122:125], v[172:175], v[4:7]
	v_mfma_f32_16x16x32_bf16 v[0:3], v[130:133], v[172:175], v[0:3]
	v_mfma_f32_16x16x32_bf16 v[0:3], v[126:129], v[168:171], v[0:3]
	s_barrier
	s_andn2_b64 vcc, exec, s[18:19]
	s_mov_b64 s[20:21], -1
	s_mov_b64 s[18:19], 0
	s_movk_i32 s26, 0x100
	s_cbranch_vccz .LBB0_1135
	s_cmpk_lt_u32 s33, 0x100
	s_cbranch_scc0 .LBB0_1138
	s_barrier

; #define PG8_STAGE(bufoff, gbase, voff) do { _Pragma("unroll") for (int _i = 0; _i < 2; ++_i) \
;         __builtin_amdgcn_global_load_lds((const unsigned*)((const char*)(gbase) + (voff)[_i]), (PG8_LAS unsigned*)(lds + (bufoff) + ldsw + _i * 8192), 16, 0, 0); } while (0)
; #define PG8_LDA(dst, b, h) do { _Pragma("unroll") for (int m = 0; m < 4; ++m) _Pragma("unroll") for (int k = 0; k < 2; ++k) dst[m][k] = *(const PG8_LAS bf16x8*)(lds + PG8_SA(b, h) + aoff + m * 2048 + k * 1024); } while (0)
; #define PG8_LDB(dst, b, h) do { _Pragma("unroll") for (int n = 0; n < 2; ++n) _Pragma("unroll") for (int k = 0; k < 2; ++k) dst[n][k] = *(const PG8_LAS bf16x8*)(lds + PG8_SB(b, h) + boff + n * 2048 + k * 1024); } while (0)
; #define PG8_MMA(ai, bj, At, Bt) do { __builtin_amdgcn_s_setprio(1); _Pragma("unroll") for (int m = 0; m < 4; ++m) _Pragma("unroll") for (int n = 0; n < 2; ++n) _Pragma("unroll") for (int k = 0; k < 2; ++k) \
;         acc[ai][bj][m][n] = __builtin_amdgcn_mfma_f32_16x16x32_bf16(Bt[n][k], At[m][k], acc[ai][bj][m][n], 0, 0, 0); __builtin_amdgcn_s_setprio(0); } while (0)
; #define PG8_WAIT_V(n) asm volatile("s_waitcnt vmcnt(" #n ")" ::: "memory")
; #define PG8_WAIT_L(n) asm volatile("s_waitcnt lgkmcnt(" #n ")" ::: "memory")
; #define PG8_BAR __builtin_amdgcn_s_barrier()
; #define PG8_SCHED __builtin_amdgcn_sched_barrier(0)
; template <class Epi, class Sched, bool ALIGN_EPI = false, bool SP2 = false>
; __device__ __forceinline__ void gemm_phase(PG8_LAS unsigned char* lds, const Gemm g, const Sched& S, const Epi& E) {
;     ...
;             PG8_LDB(B0, 0, 0); PG8_LDB(B1, 0, 1); PG8_SCHED; PG8_LDA(At, 0, 0); PG8_STAGE(PG8_SA(1, 1), a1 + hstep, voffA);
;             PG8_WAIT_V(8); PG8_WAIT_L(0); PG8_BAR; PG8_MMA(0, 0, At, B0); PG8_MMA(0, 1, At, B1); PG8_BAR; PG8_SCHED;
;             PG8_LDA(At, 0, 1); PG8_STAGE(PG8_SB(0, 0), b2, voffB); PG8_STAGE(PG8_SB(0, 1), b2 + hstep, voffB); PG8_STAGE(PG8_SA(0, 0), a2, voffA);
;             PG8_WAIT_V(8); PG8_WAIT_L(0); PG8_BAR; PG8_MMA(1, 0, At, B0); PG8_MMA(1, 1, At, B1); PG8_BAR; PG8_SCHED;
.LBB0_1404:
	ds_read_b128 v[106:109], v101
	ds_read_b128 v[110:113], v101 offset:1024
	ds_read_b128 v[114:117], v101 offset:2048
	ds_read_b128 v[118:121], v101 offset:3072
	ds_read_b128 v[122:125], v102
	ds_read_b128 v[126:129], v102 offset:1024
	ds_read_b128 v[130:133], v102 offset:2048
	ds_read_b128 v[134:137], v102 offset:3072
	s_add_u32 s14, s12, 0xe6ea0080
	s_addc_u32 s15, s13, -1
	s_cmp_lg_u32 s26, 4
	s_cselect_b32 s14, s14, 0
	s_cselect_b32 s15, s15, 0
	s_add_u32 s16, s6, s14
	s_addc_u32 s17, s7, s15
	s_add_u32 s14, s2, s14
	s_addc_u32 s15, s3, s15
	s_mov_b32 m0, s27
	v_lshl_add_u64 v[176:177], v[96:97], 0, s[12:13]
	ds_read_b128 v[150:153], v103
	ds_read_b128 v[154:157], v103 offset:1024
	ds_read_b128 v[160:163], v103 offset:2048
	ds_read_b128 v[164:167], v103 offset:3072
	ds_read_b128 v[168:171], v103 offset:4096
	ds_read_b128 v[172:175], v103 offset:5120
	ds_read_b128 v[180:183], v103 offset:6144
	ds_read_b128 v[184:187], v103 offset:7168
	global_load_lds_dwordx4 v[176:177], off
	v_lshl_add_u64 v[176:177], v[98:99], 0, s[12:13]
	s_mov_b32 m0, s28
	s_nop 0
	global_load_lds_dwordx4 v[176:177], off
	s_waitcnt vmcnt(8)
	s_waitcnt lgkmcnt(0)
	s_barrier
	s_waitcnt lgkmcnt(0)
	v_mfma_f32_16x16x32_bf16 v[92:95], v[106:109], v[150:153], v[92:95]
	v_mfma_f32_16x16x32_bf16 v[92:95], v[110:113], v[154:157], v[92:95]
	v_mfma_f32_16x16x32_bf16 v[88:91], v[118:121], v[154:157], v[88:91]
	v_mfma_f32_16x16x32_bf16 v[88:91], v[114:117], v[150:153], v[88:91]
	v_mfma_f32_16x16x32_bf16 v[72:75], v[114:117], v[160:163], v[72:75]
	v_mfma_f32_16x16x32_bf16 v[72:75], v[118:121], v[164:167], v[72:75]
	v_mfma_f32_16x16x32_bf16 v[80:83], v[110:113], v[164:167], v[80:83]
	v_mfma_f32_16x16x32_bf16 v[80:83], v[106:109], v[160:163], v[80:83]
	v_mfma_f32_16x16x32_bf16 v[64:67], v[106:109], v[168:171], v[64:67]
	v_mfma_f32_16x16x32_bf16 v[64:67], v[110:113], v[172:175], v[64:67]
	v_mfma_f32_16x16x32_bf16 v[56:59], v[118:121], v[172:175], v[56:59]
	v_mfma_f32_16x16x32_bf16 v[56:59], v[114:117], v[168:171], v[56:59]
	v_mfma_f32_16x16x32_bf16 v[40:43], v[114:117], v[180:183], v[40:43]
	v_mfma_f32_16x16x32_bf16 v[40:43], v[118:121], v[184:187], v[40:43]
	v_mfma_f32_16x16x32_bf16 v[48:51], v[110:113], v[184:187], v[48:51]
	v_mfma_f32_16x16x32_bf16 v[48:51], v[106:109], v[180:183], v[48:51]
	v_mfma_f32_16x16x32_bf16 v[84:87], v[122:125], v[150:153], v[84:87]
	v_mfma_f32_16x16x32_bf16 v[84:87], v[126:129], v[154:157], v[84:87]
	v_mfma_f32_16x16x32_bf16 v[76:79], v[134:137], v[154:157], v[76:79]
	v_mfma_f32_16x16x32_bf16 v[76:79], v[130:133], v[150:153], v[76:79]
	v_mfma_f32_16x16x32_bf16 v[60:63], v[130:133], v[160:163], v[60:63]
	v_mfma_f32_16x16x32_bf16 v[60:63], v[134:137], v[164:167], v[60:63]
	v_mfma_f32_16x16x32_bf16 v[68:71], v[126:129], v[164:167], v[68:71]
	v_mfma_f32_16x16x32_bf16 v[68:71], v[122:125], v[160:163], v[68:71]
	v_mfma_f32_16x16x32_bf16 v[52:55], v[122:125], v[168:171], v[52:55]
	v_mfma_f32_16x16x32_bf16 v[52:55], v[126:129], v[172:175], v[52:55]
	v_mfma_f32_16x16x32_bf16 v[44:47], v[134:137], v[172:175], v[44:47]
	v_mfma_f32_16x16x32_bf16 v[44:47], v[130:133], v[168:171], v[44:47]
	v_mfma_f32_16x16x32_bf16 v[32:35], v[130:133], v[180:183], v[32:35]
	v_mfma_f32_16x16x32_bf16 v[32:35], v[134:137], v[184:187], v[32:35]
	v_mfma_f32_16x16x32_bf16 v[36:39], v[126:129], v[184:187], v[36:39]
	v_mfma_f32_16x16x32_bf16 v[36:39], v[122:125], v[180:183], v[36:39]
	s_barrier
	s_mov_b32 m0, s29
	v_lshl_add_u64 v[176:177], s[14:15], 0, v[144:145]
	s_add_u32 s38, s14, 0x160000
	ds_read_b128 v[150:153], v103 offset:16384
	ds_read_b128 v[154:157], v103 offset:17408
	ds_read_b128 v[160:163], v103 offset:18432
	ds_read_b128 v[164:167], v103 offset:19456
	global_load_lds_dwordx4 v[176:177], off
	v_lshl_add_u64 v[188:189], s[14:15], 0, v[148:149]
	s_mov_b32 m0, s30
	s_addc_u32 s39, s15, 0
	global_load_lds_dwordx4 v[188:189], off
	v_lshl_add_u64 v[168:169], s[38:39], 0, v[144:145]
	s_mov_b32 m0, s31
	v_lshl_add_u64 v[190:191], s[16:17], 0, v[142:143]
	global_load_lds_dwordx4 v[168:169], off
	v_lshl_add_u64 v[168:169], s[38:39], 0, v[148:149]
	s_mov_b32 m0, s33
	v_lshl_add_u64 v[192:193], s[16:17], 0, v[146:147]
	global_load_lds_dwordx4 v[168:169], off
	s_mov_b32 m0, s5
	s_nop 0
	global_load_lds_dwordx4 v[190:191], off
	s_mov_b32 m0, s20
	s_nop 0
	global_load_lds_dwordx4 v[192:193], off
	s_waitcnt vmcnt(8)
	s_waitcnt lgkmcnt(0)
	s_barrier
	s_waitcnt lgkmcnt(0)
	v_mfma_f32_16x16x32_bf16 v[28:31], v[106:109], v[150:153], v[28:31]
	v_mfma_f32_16x16x32_bf16 v[28:31], v[110:113], v[154:157], v[28:31]
	v_mfma_f32_16x16x32_bf16 v[24:27], v[118:121], v[154:157], v[24:27]
	v_mfma_f32_16x16x32_bf16 v[24:27], v[114:117], v[150:153], v[24:27]
	v_mfma_f32_16x16x32_bf16 v[12:15], v[106:109], v[160:163], v[12:15]
	v_mfma_f32_16x16x32_bf16 v[12:15], v[110:113], v[164:167], v[12:15]
	v_mfma_f32_16x16x32_bf16 v[8:11], v[118:121], v[164:167], v[8:11]
	v_mfma_f32_16x16x32_bf16 v[8:11], v[114:117], v[160:163], v[8:11]
	v_mfma_f32_16x16x32_bf16 v[20:23], v[122:125], v[150:153], v[20:23]
	v_mfma_f32_16x16x32_bf16 v[20:23], v[126:129], v[154:157], v[20:23]
	v_mfma_f32_16x16x32_bf16 v[16:19], v[134:137], v[154:157], v[16:19]
	v_mfma_f32_16x16x32_bf16 v[16:19], v[130:133], v[150:153], v[16:19]
	v_mfma_f32_16x16x32_bf16 v[4:7], v[122:125], v[160:163], v[4:7]
	v_mfma_f32_16x16x32_bf16 v[4:7], v[126:129], v[164:167], v[4:7]
	v_mfma_f32_16x16x32_bf16 v[0:3], v[134:137], v[164:167], v[0:3]
	v_mfma_f32_16x16x32_bf16 v[0:3], v[130:133], v[160:163], v[0:3]
	s_barrier
; #define PG8_STAGE(bufoff, gbase, voff) do { _Pragma("unroll") for (int _i = 0; _i < 2; ++_i) \
;         __builtin_amdgcn_global_load_lds((const unsigned*)((const char*)(gbase) + (voff)[_i]), (PG8_LAS unsigned*)(lds + (bufoff) + ldsw + _i * 8192), 16, 0, 0); } while (0)
; #define PG8_LDA(dst, b, h) do { _Pragma("unroll") for (int m = 0; m < 4; ++m) _Pragma("unroll") for (int k = 0; k < 2; ++k) dst[m][k] = *(const PG8_LAS bf16x8*)(lds + PG8_SA(b, h) + aoff + m * 2048 + k * 1024); } while (0)
; #define PG8_LDB(dst, b, h) do { _Pragma("unroll") for (int n = 0; n < 2; ++n) _Pragma("unroll") for (int k = 0; k < 2; ++k) dst[n][k] = *(const PG8_LAS bf16x8*)(lds + PG8_SB(b, h) + boff + n * 2048 + k * 1024); } while (0)
; #define PG8_MMA(ai, bj, At, Bt) do { __builtin_amdgcn_s_setprio(1); _Pragma("unroll") for (int m = 0; m < 4; ++m) _Pragma("unroll") for (int n = 0; n < 2; ++n) _Pragma("unroll") for (int k = 0; k < 2; ++k) \
;         acc[ai][bj][m][n] = __builtin_amdgcn_mfma_f32_16x16x32_bf16(Bt[n][k], At[m][k], acc[ai][bj][m][n], 0, 0, 0); __builtin_amdgcn_s_setprio(0); } while (0)
; #define PG8_WAIT_V(n) asm volatile("s_waitcnt vmcnt(" #n ")" ::: "memory")
; #define PG8_WAIT_L(n) asm volatile("s_waitcnt lgkmcnt(" #n ")" ::: "memory")
; #define PG8_BAR __builtin_amdgcn_s_barrier()
; #define PG8_SCHED __builtin_amdgcn_sched_barrier(0)
; template <class Epi, class Sched, bool ALIGN_EPI = false, bool SP2 = false>
; __device__ __forceinline__ void gemm_phase(PG8_LAS unsigned char* lds, const Gemm g, const Sched& S, const Epi& E) {
;     ...
;             PG8_LDB(B0, 1, 0); PG8_LDB(B1, 1, 1); PG8_SCHED; PG8_LDA(At, 1, 0); PG8_STAGE(PG8_SA(0, 1), a2 + hstep, voffA);
;             PG8_WAIT_V(8); PG8_WAIT_L(0); PG8_BAR; PG8_MMA(0, 0, At, B0); PG8_MMA(0, 1, At, B1); PG8_BAR; PG8_SCHED;
;             PG8_LDA(At, 1, 1); PG8_STAGE(PG8_SB(1, 0), b3, voffB); PG8_STAGE(PG8_SB(1, 1), b3 + hstep, voffB); PG8_STAGE(PG8_SA(1, 0), a3, voffA);
;             PG8_WAIT_V(8); PG8_WAIT_L(0); PG8_BAR; PG8_MMA(1, 0, At, B0); PG8_MMA(1, 1, At, B1); PG8_BAR; PG8_SCHED;
	ds_read_b128 v[106:109], v104
	ds_read_b128 v[110:113], v104 offset:1024
	ds_read_b128 v[114:117], v104 offset:2048
	ds_read_b128 v[118:121], v104 offset:3072
	ds_read_b128 v[122:125], v105
	ds_read_b128 v[126:129], v105 offset:1024
	ds_read_b128 v[130:133], v105 offset:2048
	ds_read_b128 v[134:137], v105 offset:3072
	s_add_u32 s16, s16, 0x160000
	s_addc_u32 s17, s17, 0
	s_mov_b32 m0, s21
	v_lshl_add_u64 v[194:195], s[16:17], 0, v[142:143]
	ds_read_b128 v[150:153], v103 offset:32768
	ds_read_b128 v[154:157], v103 offset:33792
	ds_read_b128 v[160:163], v103 offset:34816
	ds_read_b128 v[164:167], v103 offset:35840
	ds_read_b128 v[168:171], v103 offset:36864
	ds_read_b128 v[172:175], v103 offset:37888
	ds_read_b128 v[180:183], v103 offset:38912
	ds_read_b128 v[184:187], v103 offset:39936
	global_load_lds_dwordx4 v[194:195], off
	v_lshl_add_u64 v[194:195], s[16:17], 0, v[146:147]
	s_mov_b32 m0, s22
	s_nop 0
	global_load_lds_dwordx4 v[194:195], off
	s_waitcnt vmcnt(8)
	s_waitcnt lgkmcnt(0)
	s_barrier
	s_waitcnt lgkmcnt(0)
	v_mfma_f32_16x16x32_bf16 v[92:95], v[106:109], v[150:153], v[92:95]
	v_mfma_f32_16x16x32_bf16 v[92:95], v[110:113], v[154:157], v[92:95]
	v_mfma_f32_16x16x32_bf16 v[88:91], v[118:121], v[154:157], v[88:91]
	v_mfma_f32_16x16x32_bf16 v[88:91], v[114:117], v[150:153], v[88:91]
	v_mfma_f32_16x16x32_bf16 v[72:75], v[114:117], v[160:163], v[72:75]
	v_mfma_f32_16x16x32_bf16 v[72:75], v[118:121], v[164:167], v[72:75]
	v_mfma_f32_16x16x32_bf16 v[80:83], v[110:113], v[164:167], v[80:83]
	v_mfma_f32_16x16x32_bf16 v[80:83], v[106:109], v[160:163], v[80:83]
	v_mfma_f32_16x16x32_bf16 v[64:67], v[106:109], v[168:171], v[64:67]
	v_mfma_f32_16x16x32_bf16 v[64:67], v[110:113], v[172:175], v[64:67]
	v_mfma_f32_16x16x32_bf16 v[56:59], v[118:121], v[172:175], v[56:59]
	v_mfma_f32_16x16x32_bf16 v[56:59], v[114:117], v[168:171], v[56:59]
	v_mfma_f32_16x16x32_bf16 v[40:43], v[114:117], v[180:183], v[40:43]
	v_mfma_f32_16x16x32_bf16 v[40:43], v[118:121], v[184:187], v[40:43]
	v_mfma_f32_16x16x32_bf16 v[48:51], v[110:113], v[184:187], v[48:51]
	v_mfma_f32_16x16x32_bf16 v[48:51], v[106:109], v[180:183], v[48:51]
	v_mfma_f32_16x16x32_bf16 v[84:87], v[122:125], v[150:153], v[84:87]
	v_mfma_f32_16x16x32_bf16 v[84:87], v[126:129], v[154:157], v[84:87]
	v_mfma_f32_16x16x32_bf16 v[76:79], v[134:137], v[154:157], v[76:79]
	v_mfma_f32_16x16x32_bf16 v[76:79], v[130:133], v[150:153], v[76:79]
	v_mfma_f32_16x16x32_bf16 v[60:63], v[130:133], v[160:163], v[60:63]
	v_mfma_f32_16x16x32_bf16 v[60:63], v[134:137], v[164:167], v[60:63]
	v_mfma_f32_16x16x32_bf16 v[68:71], v[126:129], v[164:167], v[68:71]
	v_mfma_f32_16x16x32_bf16 v[68:71], v[122:125], v[160:163], v[68:71]
	v_mfma_f32_16x16x32_bf16 v[52:55], v[122:125], v[168:171], v[52:55]
	v_mfma_f32_16x16x32_bf16 v[52:55], v[126:129], v[172:175], v[52:55]
	v_mfma_f32_16x16x32_bf16 v[44:47], v[134:137], v[172:175], v[44:47]
	v_mfma_f32_16x16x32_bf16 v[44:47], v[130:133], v[168:171], v[44:47]
	v_mfma_f32_16x16x32_bf16 v[32:35], v[130:133], v[180:183], v[32:35]
	v_mfma_f32_16x16x32_bf16 v[32:35], v[134:137], v[184:187], v[32:35]
	v_mfma_f32_16x16x32_bf16 v[36:39], v[126:129], v[184:187], v[36:39]
	v_mfma_f32_16x16x32_bf16 v[36:39], v[122:125], v[180:183], v[36:39]
	s_barrier
	s_mov_b32 m0, s34
	v_lshl_add_u64 v[168:169], v[176:177], 0, s[10:11]
	s_add_u32 s14, s14, 0x160080
	ds_read_b128 v[150:153], v103 offset:49152
	ds_read_b128 v[154:157], v103 offset:50176
	ds_read_b128 v[160:163], v103 offset:51200
	ds_read_b128 v[164:167], v103 offset:52224
	global_load_lds_dwordx4 v[168:169], off
	v_lshl_add_u64 v[168:169], v[188:189], 0, s[10:11]
	s_mov_b32 m0, s35
	s_addc_u32 s15, s15, 0
	global_load_lds_dwordx4 v[168:169], off
	v_lshl_add_u64 v[168:169], s[14:15], 0, v[144:145]
	s_mov_b32 m0, s36
	s_nop 0
	global_load_lds_dwordx4 v[168:169], off
	v_lshl_add_u64 v[168:169], s[14:15], 0, v[148:149]
	s_mov_b32 m0, s37
	s_nop 0
	global_load_lds_dwordx4 v[168:169], off
	v_lshl_add_u64 v[168:169], v[190:191], 0, s[10:11]
	s_mov_b32 m0, s24
	s_nop 0
	global_load_lds_dwordx4 v[168:169], off
	v_lshl_add_u64 v[168:169], v[192:193], 0, s[10:11]
	s_mov_b32 m0, s25
	s_nop 0
	global_load_lds_dwordx4 v[168:169], off
	s_waitcnt vmcnt(8)
	s_waitcnt lgkmcnt(0)
	s_barrier
	s_waitcnt lgkmcnt(0)
	v_mfma_f32_16x16x32_bf16 v[28:31], v[106:109], v[150:153], v[28:31]
	v_mfma_f32_16x16x32_bf16 v[28:31], v[110:113], v[154:157], v[28:31]
	v_mfma_f32_16x16x32_bf16 v[24:27], v[118:121], v[154:157], v[24:27]
	v_mfma_f32_16x16x32_bf16 v[24:27], v[114:117], v[150:153], v[24:27]
	v_mfma_f32_16x16x32_bf16 v[12:15], v[106:109], v[160:163], v[12:15]
	v_mfma_f32_16x16x32_bf16 v[12:15], v[110:113], v[164:167], v[12:15]
	v_mfma_f32_16x16x32_bf16 v[8:11], v[118:121], v[164:167], v[8:11]
	v_mfma_f32_16x16x32_bf16 v[8:11], v[114:117], v[160:163], v[8:11]
	v_mfma_f32_16x16x32_bf16 v[20:23], v[122:125], v[150:153], v[20:23]
	v_mfma_f32_16x16x32_bf16 v[20:23], v[126:129], v[154:157], v[20:23]
	v_mfma_f32_16x16x32_bf16 v[16:19], v[134:137], v[154:157], v[16:19]
	v_mfma_f32_16x16x32_bf16 v[16:19], v[130:133], v[150:153], v[16:19]
	v_mfma_f32_16x16x32_bf16 v[4:7], v[122:125], v[160:163], v[4:7]
	v_mfma_f32_16x16x32_bf16 v[4:7], v[126:129], v[164:167], v[4:7]
	v_mfma_f32_16x16x32_bf16 v[0:3], v[134:137], v[164:167], v[0:3]
	v_mfma_f32_16x16x32_bf16 v[0:3], v[130:133], v[160:163], v[0:3]
	s_barrier
	s_add_i32 s26, s26, 2
	s_add_u32 s12, s12, 0x100
	s_addc_u32 s13, s13, 0
	s_cmp_gt_u32 s26, 5
	s_cbranch_scc0 .LBB0_1404
	s_cmpk_lt_u32 s18, 0x100
	s_cbranch_scc0 .LBB0_1407
	s_barrier
